# v16: v14 + per-tile unit decode without the runtime division (gsz is always 8): 32 fewer instructions per tile in all four GEMM phases
# speedup vs baseline: 1.0253x; 1.0096x over previous
; #define PG8_STAGE(bufoff, gbase, voff) do { _Pragma("unroll") for (int _i = 0; _i < 2; ++_i) \
;         __builtin_amdgcn_global_load_lds((const unsigned*)((const char*)(gbase) + (voff)[_i]), (LAS unsigned*)(lds + (bufoff) + ldsw + _i * 8192), 16, 0, 0); } while (0)
; #define PG8_WAIT_V(n) asm volatile("s_waitcnt vmcnt(" #n ")" ::: "memory")
; #define PG8_BAR __builtin_amdgcn_s_barrier()
; template <class Epi, class Ptrs>
; __device__ __forceinline__ void gemm_phase(LAS unsigned char* lds, const int K, const StaticOrder& S, const Ptrs& P, const Epi& E) {
;     ...
;     PG8_STAGE(PG8_SB(0, 0), cB, voffB); PG8_STAGE(PG8_SA(0, 0), cA, voffA); PG8_STAGE(PG8_SB(0, 1), cB + hstep, voffB); PG8_STAGE(PG8_SA(0, 1), cA + hstep, voffA);
;     if (wr == 1) PG8_BAR;
;     PG8_WAIT_V(4); PG8_BAR;
;     PG8_STAGE(PG8_SB(1, 0), cB + kstep, voffB); PG8_STAGE(PG8_SA(1, 0), cA + kstep, voffA); PG8_STAGE(PG8_SB(1, 1), cB + hstep + kstep, voffB);
;     PG8_WAIT_V(6); PG8_BAR;
;     for (;;) {
;         const bool has_next = S.next(ui + 1, nxt);
;         const char* nA = cA; const char* nB = cB; if (has_next) P.get(nxt, nA, nB);
.LBB0_120:
	s_add_u32 s4, s28, 0x35000000
	s_addc_u32 s5, s29, 0
	s_mov_b64 s[58:59], 0x80
	v_writelane_b32 v254, s4, 0
	v_lshl_add_u64 v[6:7], v[6:7], 0, s[58:59]
	s_waitcnt vmcnt(4)
	s_barrier
	v_writelane_b32 v254, s5, 1
	s_add_u32 s4, s28, 0x26000000
	s_addc_u32 s5, s29, 0
	s_add_u32 s42, s28, 0x32000000
	s_addc_u32 s43, s29, 0
	s_add_u32 s44, s28, 0x2000000
	s_addc_u32 s45, s29, 0
	s_add_u32 s48, s26, 0xc000000
	s_addc_u32 s49, s27, 0
	s_add_u32 s54, s28, 0x3e000000
	s_addc_u32 s55, s29, 0
	s_add_u32 s56, s28, 0xe000000
	s_addc_u32 s57, s29, 0
	s_lshl_b32 s1, s1, 5
	s_and_b32 s88, s1, 0x60
	s_add_i32 m0, s67, 0x18000
	v_writelane_b32 v254, s4, 2
	s_ashr_i32 s86, s3, 31
	s_ashr_i32 s87, s2, 31
	s_lshl_b32 s20, s0, 13
	s_lshl_b32 s1, s88, 7
	global_load_lds_dwordx4 v[6:7], off
	v_lshl_add_u64 v[4:5], v[4:5], 0, s[58:59]
	s_add_i32 m0, s67, 0x1a000
	s_add_i32 s89, s67, 0x8000
	s_add_i32 s90, s67, 0xa000
	v_writelane_b32 v254, s5, 3
	global_load_lds_dwordx4 v[4:5], off
	v_lshl_add_u64 v[2:3], v[2:3], 0, s[58:59]
	s_mov_b32 m0, s89
	s_add_u32 s4, s78, 0x40080
	global_load_lds_dwordx4 v[2:3], off
	v_lshl_add_u64 v[0:1], v[0:1], 0, s[58:59]
	s_mov_b32 m0, s90
	s_addc_u32 s5, s79, 0
	global_load_lds_dwordx4 v[0:1], off
	s_add_i32 m0, s67, 0x1c000
	v_lshl_add_u64 v[0:1], s[4:5], 0, v[134:135]
	global_load_lds_dwordx4 v[0:1], off
	v_lshl_add_u64 v[0:1], s[4:5], 0, v[138:139]
	s_add_i32 m0, s67, 0x1e000
	v_lshlrev_b32_e32 v2, 6, v208
	global_load_lds_dwordx4 v[0:1], off
	v_and_b32_e32 v0, 15, v208
	v_lshlrev_b32_e32 v1, 1, v130
	s_movk_i32 s4, 0x3c0
	v_lshlrev_b32_e32 v3, 2, v208
	v_and_or_b32 v2, v2, s4, v1
	v_and_b32_e32 v3, 32, v3
	v_cmp_eq_u32_e64 s[10:11], 0, v0
	v_lshl_or_b32 v129, s0, 6, v0
	v_lshl_or_b32 v0, v0, 6, v1
	v_lshlrev_b32_e32 v1, 8, v208
	v_bitop3_b32 v131, s1, v2, v3 bitop3:0xf6
	v_and_b32_e32 v1, 0x38000, v1
	v_lshlrev_b32_e32 v2, 11, v10
	v_or3_b32 v1, v8, v1, v2
	v_add_u32_e32 v142, v1, v9
	v_lshlrev_b32_e32 v1, 4, v11
	s_waitcnt vmcnt(6)
	v_and_b32_e32 v1, 0x78000, v1
	v_bitop3_b32 v0, v0, s20, v3 bitop3:0xde
	v_or3_b32 v1, v8, v1, v2
	s_add_i32 s91, 0, 0x10000
	s_add_i32 s92, 0, 0x14000
	v_or_b32_e32 v204, s88, v130
	v_mov_b32_e32 v143, v141
	v_add_u32_e32 v144, v1, v9
	v_mov_b32_e32 v145, v141
	v_mov_b64_e32 v[146:147], 0x2100
	v_mov_b64_e32 v[148:149], 0x20ff
	v_add_u32_e32 v205, s91, v131
	v_add_u32_e32 v206, 0, v0
	v_add_u32_e32 v207, s92, v131
	s_mov_b32 s60, 0xbfb8aa3b
	s_lshl_b32 s62, s0, 2
	s_mov_b32 s64, 0x3dd2d3e7
	s_mov_b32 s66, 0xc0135761
	s_mov_b32 s93, 0x600000
	s_mov_b32 s94, 0x900000
	s_mov_b32 s95, 0x1800000
	s_mov_b32 s96, 0x1b00000
	s_mov_b32 s97, 0x1e00000
	s_mov_b32 s98, 0x2100000
	s_mov_b32 s99, 0x40000
	s_mov_b32 s22, 0x48000
	s_mov_b32 s23, 0x50000
	s_nop 0
	s_nop 0
	s_nop 0
	s_nop 0
	s_nop 0
	s_nop 0
	s_nop 0
	s_nop 0
	s_nop 0
	s_nop 0
	s_nop 0
	s_nop 0
	s_nop 0
	s_nop 0
	s_nop 0
	s_nop 0
	s_nop 0
	s_nop 0
	s_nop 0
	s_nop 0
	s_nop 0
	s_nop 0
	s_nop 0
	s_nop 0
	s_nop 0
	s_nop 0
	s_nop 0
	s_nop 0
	s_nop 0
	s_nop 0
	s_nop 0
	s_nop 0
	s_nop 0
	s_nop 0
	s_nop 0
	s_nop 0
	s_nop 0
	s_nop 0
	s_nop 0
	s_nop 0
	s_nop 0
	s_nop 0
	s_nop 0
	s_nop 0
	s_nop 0
	s_nop 0
	s_nop 0
	s_nop 0
	s_nop 0
	s_nop 0
	s_nop 0
	s_nop 0
	s_nop 0
	s_nop 0
	s_nop 0
	s_mov_b32 s24, 0
	s_cmpk_lt_u32 s61, 0x100
	s_cbranch_scc1 .Lsprio_0
	s_setprio 1

;     __device__ bool next(int i, Unit& u) const {
;         if (rev && i >= rev) return false;
;         const long L = (long)(rev ? rev - 1 - i : i) * G + c; if (L >= nwg) return false;
;         int wgid = (int)L; { const int q = nwg / NXCD, r = nwg % NXCD, xcd = wgid % NXCD, off = wgid / NXCD; wgid = (xcd < r ? xcd * (q + 1) : r * (q + 1) + (xcd - r) * q) + off; }
;         const int nig = WGM * nN, gid = wgid / nig, fm = gid * WGM, gsz = (nM - fm) < WGM ? (nM - fm) : WGM;
;         u.pm = fm + ((wgid % nig) % gsz); u.pn = (wgid % nig) / gsz; return true;
.LBB0_122:
	s_add_i32 s24, s24, 1
	s_mul_i32 s0, s24, s86
	s_mul_hi_u32 s1, s24, s3
	s_add_i32 s1, s1, s0
	s_mul_i32 s0, s24, s3
	s_add_u32 s72, s0, s2
	s_addc_u32 s73, s1, s87
	v_cmp_gt_i64_e64 s[4:5], s[72:73], v[148:149]
	v_cmp_lt_i64_e64 s[0:1], s[72:73], v[146:147]
	s_and_b64 vcc, exec, s[4:5]
	s_cbranch_vccnz .LBB0_124
	s_ashr_i32 s20, s72, 31
	s_lshr_b32 s20, s20, 29
	s_add_i32 s20, s72, s20
	s_ashr_i32 s25, s20, 3
	s_and_b32 s20, s20, -8
	s_sub_i32 s20, s72, s20
	s_cmp_lt_i32 s20, 0
	s_movk_i32 s63, 0x421
	s_cselect_b32 s63, s63, 0x420
	s_mul_i32 s20, s20, s63
	s_add_i32 s20, s20, s25
	s_mul_hi_i32 s25, s20, 0x2e8ba2e9
	s_lshr_b32 s63, s25, 31
	s_ashr_i32 s25, s25, 5
	s_add_i32 s25, s25, s63
	s_lshl_b32 s63, s25, 3
	s_mulk_i32 s25, 0xb0
	s_sub_i32 s20, s20, s25
	s_lshr_b32 s68, s20, 3
	s_and_b32 s20, s20, 7
	s_add_i32 s70, s63, s20

; #define PG8_STAGE(bufoff, gbase, voff) do { _Pragma("unroll") for (int _i = 0; _i < 2; ++_i) \
;         __builtin_amdgcn_global_load_lds((const unsigned*)((const char*)(gbase) + (voff)[_i]), (LAS unsigned*)(lds + (bufoff) + ldsw + _i * 8192), 16, 0, 0); } while (0)
; #define PG8_WAIT_V(n) asm volatile("s_waitcnt vmcnt(" #n ")" ::: "memory")
; #define PG8_BAR __builtin_amdgcn_s_barrier()
; template <class Epi, class Ptrs>
; __device__ __forceinline__ void gemm_phase(LAS unsigned char* lds, const int K, const StaticOrder& S, const Ptrs& P, const Epi& E) {
;     ...
;     PG8_STAGE(PG8_SB(0, 0), cB, voffB); PG8_STAGE(PG8_SA(0, 0), cA, voffA); PG8_STAGE(PG8_SB(0, 1), cB + hstep, voffB); PG8_STAGE(PG8_SA(0, 1), cA + hstep, voffA);
;     if (wr == 1) PG8_BAR;
;     PG8_WAIT_V(4); PG8_BAR;
;     PG8_STAGE(PG8_SB(1, 0), cB + kstep, voffB); PG8_STAGE(PG8_SA(1, 0), cA + kstep, voffA); PG8_STAGE(PG8_SB(1, 1), cB + hstep + kstep, voffB);
;     PG8_WAIT_V(6); PG8_BAR;
;     for (;;) {
;         const bool has_next = S.next(ui + 1, nxt);
;         const char* nA = cA; const char* nB = cB; if (has_next) P.get(nxt, nA, nB);
.LBB0_346:
	s_add_u32 s14, s28, 0x2000000
	s_addc_u32 s15, s29, 0
	s_add_u32 s16, s28, 0x3e000000
	s_addc_u32 s17, s29, 0
	s_ashr_i32 s58, s3, 31
	s_ashr_i32 s59, s2, 31
	s_add_u32 s60, s38, 0xf8000000
	s_mov_b64 s[18:19], 0x80
	s_addc_u32 s61, s39, -1
	s_and_b32 s62, s1, 3
	s_add_i32 m0, s54, 0x18000
	v_lshl_add_u64 v[6:7], v[6:7], 0, s[18:19]
	s_lshl_b32 s1, s0, 13
	s_lshl_b32 s20, s62, 12
	s_waitcnt vmcnt(4)
	s_barrier
	global_load_lds_dwordx4 v[6:7], off
	v_lshl_add_u64 v[4:5], v[4:5], 0, s[18:19]
	s_add_i32 m0, s54, 0x1a000
	s_add_i32 s63, s54, 0x8000
	s_add_i32 s64, s54, 0xa000
	global_load_lds_dwordx4 v[4:5], off
	v_lshl_add_u64 v[2:3], v[2:3], 0, s[18:19]
	s_mov_b32 m0, s63
	s_add_u32 s4, s42, 0x40080
	global_load_lds_dwordx4 v[2:3], off
	v_lshl_add_u64 v[0:1], v[0:1], 0, s[18:19]
	s_mov_b32 m0, s64
	s_addc_u32 s5, s43, 0
	global_load_lds_dwordx4 v[0:1], off
	s_add_i32 m0, s54, 0x1c000
	v_lshl_add_u64 v[0:1], s[4:5], 0, v[178:179]
	global_load_lds_dwordx4 v[0:1], off
	v_lshl_add_u64 v[0:1], s[4:5], 0, v[182:183]
	s_add_i32 m0, s54, 0x1e000
	v_lshlrev_b32_e32 v4, 6, v208
	global_load_lds_dwordx4 v[0:1], off
	v_bfe_u32 v1, v208, 4, 2
	v_lshlrev_b32_e32 v2, 3, v1
	v_lshlrev_b32_e32 v3, 4, v1
	v_cmp_eq_u32_e64 s[6:7], 0, v1
	v_lshlrev_b32_e32 v1, 8, v208
	v_lshl_or_b32 v206, s62, 5, v2
	v_and_b32_e32 v1, 0x38000, v1
	v_lshlrev_b32_e32 v2, 11, v10
	v_or3_b32 v1, v8, v1, v2
	v_and_b32_e32 v0, 15, v208
	s_movk_i32 s4, 0x3c0
	v_lshlrev_b32_e32 v5, 2, v208
	v_add_u32_e32 v184, v1, v9
	v_lshlrev_b32_e32 v1, 4, v11
	v_and_or_b32 v4, v4, s4, v3
	v_and_b32_e32 v5, 32, v5
	v_lshl_or_b32 v204, s0, 6, v0
	v_lshl_or_b32 v0, v0, 6, v3
	s_waitcnt vmcnt(6)
	v_and_b32_e32 v1, 0x78000, v1
	v_bitop3_b32 v0, v0, s1, v5 bitop3:0xde
	v_bitop3_b32 v205, s20, v4, v5 bitop3:0xf6
	v_or3_b32 v1, v8, v1, v2
	s_add_i32 s66, 0, 0x10000
	s_add_i32 s67, 0, 0x14000
	v_mov_b32_e32 v185, v179
	v_add_u32_e32 v186, v1, v9
	v_mov_b32_e32 v187, v179
	v_mov_b64_e32 v[188:189], 0x600
	v_mov_b64_e32 v[190:191], 0x5ff
	s_movk_i32 s65, 0xc1
	v_add_u32_e32 v207, s66, v205
	v_add_u32_e32 v209, 0, v0
	v_add_u32_e32 v210, s67, v205
	s_nop 0
	s_nop 0
	s_nop 0
	s_nop 0
	s_nop 0
	s_nop 0
	s_nop 0
	s_nop 0
	s_nop 0
	s_nop 0
	s_nop 0
	s_nop 0
	s_nop 0
	s_nop 0
	s_nop 0
	s_nop 0
	s_nop 0
	s_nop 0
	s_nop 0
	s_nop 0
	s_nop 0
	s_nop 0
	s_nop 0
	s_nop 0
	s_nop 0
	s_nop 0
	s_nop 0
	s_nop 0
	s_nop 0
	s_nop 0
	s_nop 0
	s_nop 0
	s_nop 0
	s_nop 0
	s_nop 0
	s_nop 0
	s_nop 0
	s_nop 0
	s_nop 0
	s_nop 0
	s_nop 0
	s_nop 0
	s_nop 0
	s_nop 0
	s_nop 0
	s_nop 0
	s_nop 0
	s_nop 0
	s_nop 0
	s_nop 0
	s_nop 0
	s_nop 0
	s_nop 0
	s_nop 0
	s_nop 0
	s_mov_b32 s68, 0
	s_cmpk_lt_u32 s46, 0x100
	s_cbranch_scc1 .Lsprio_1
	s_setprio 1

;     __device__ bool next(int i, Unit& u) const {
;         if (rev && i >= rev) return false;
;         const long L = (long)(rev ? rev - 1 - i : i) * G + c; if (L >= nwg) return false;
;         int wgid = (int)L; { const int q = nwg / NXCD, r = nwg % NXCD, xcd = wgid % NXCD, off = wgid / NXCD; wgid = (xcd < r ? xcd * (q + 1) : r * (q + 1) + (xcd - r) * q) + off; }
;         const int nig = WGM * nN, gid = wgid / nig, fm = gid * WGM, gsz = (nM - fm) < WGM ? (nM - fm) : WGM;
;         u.pm = fm + ((wgid % nig) % gsz); u.pn = (wgid % nig) / gsz; return true;
.LBB0_348:
	s_add_i32 s68, s68, 1
	s_mul_i32 s0, s68, s58
	s_mul_hi_u32 s1, s68, s3
	s_add_i32 s1, s1, s0
	s_mul_i32 s0, s68, s3
	s_add_u32 s24, s0, s2
	s_addc_u32 s25, s1, s59
	v_cmp_gt_i64_e64 s[4:5], s[24:25], v[190:191]
	v_cmp_lt_i64_e64 s[0:1], s[24:25], v[188:189]
	s_and_b64 vcc, exec, s[4:5]
	s_cbranch_vccnz .LBB0_350
	s_ashr_i32 s20, s24, 31
	s_lshr_b32 s20, s20, 29
	s_add_i32 s20, s24, s20
	s_ashr_i32 s21, s20, 3
	s_and_b32 s20, s20, -8
	s_sub_i32 s20, s24, s20
	s_cmp_lt_i32 s20, 0
	s_cselect_b32 s22, s65, 0xc0
	s_mul_i32 s20, s20, s22
	s_add_i32 s20, s20, s21
	s_ashr_i32 s21, s20, 31
	s_lshr_b32 s21, s21, 27
	s_add_i32 s21, s20, s21
	s_ashr_i32 s22, s21, 5
	s_lshl_b32 s22, s22, 3
	s_andn2_b32 s21, s21, 31
	s_sub_i32 s21, s20, s21
	s_lshr_b32 s20, s21, 3
	s_and_b32 s21, s21, 7
	s_add_i32 s22, s22, s21

; #define PG8_STAGE(bufoff, gbase, voff) do { _Pragma("unroll") for (int _i = 0; _i < 2; ++_i) \
;         __builtin_amdgcn_global_load_lds((const unsigned*)((const char*)(gbase) + (voff)[_i]), (LAS unsigned*)(lds + (bufoff) + ldsw + _i * 8192), 16, 0, 0); } while (0)
; #define PG8_WAIT_V(n) asm volatile("s_waitcnt vmcnt(" #n ")" ::: "memory")
; #define PG8_BAR __builtin_amdgcn_s_barrier()
; template <class Epi, class Ptrs>
; __device__ __forceinline__ void gemm_phase(LAS unsigned char* lds, const int K, const StaticOrder& S, const Ptrs& P, const Epi& E) {
;     ...
;     PG8_STAGE(PG8_SB(0, 0), cB, voffB); PG8_STAGE(PG8_SA(0, 0), cA, voffA); PG8_STAGE(PG8_SB(0, 1), cB + hstep, voffB); PG8_STAGE(PG8_SA(0, 1), cA + hstep, voffA);
;     if (wr == 1) PG8_BAR;
;     PG8_WAIT_V(4); PG8_BAR;
;     PG8_STAGE(PG8_SB(1, 0), cB + kstep, voffB); PG8_STAGE(PG8_SA(1, 0), cA + kstep, voffA); PG8_STAGE(PG8_SB(1, 1), cB + hstep + kstep, voffB);
;     PG8_WAIT_V(6); PG8_BAR;
;     for (;;) {
;         const bool has_next = S.next(ui + 1, nxt);
;         const char* nA = cA; const char* nB = cB; if (has_next) P.get(nxt, nA, nB);
.LBB0_427:
	s_nop 0
	s_nop 0
	s_nop 0
	s_nop 0
	s_nop 0
	s_nop 0
	s_nop 0
	s_nop 0
	s_nop 0
	s_nop 0
	s_nop 0
	s_nop 0
	s_nop 0
	s_nop 0
	s_nop 0
	s_nop 0
	s_nop 0
	s_nop 0
	s_nop 0
	s_nop 0
	s_nop 0
	s_nop 0
	s_nop 0
	s_nop 0
	s_nop 0
	s_nop 0
	s_nop 0
	s_nop 0
	s_nop 0
	s_nop 0
	s_nop 0
	s_nop 0
	s_nop 0
	s_nop 0
	s_nop 0
	s_nop 0
	s_nop 0
	s_nop 0
	s_nop 0
	s_nop 0
	s_nop 0
	s_nop 0
	s_nop 0
	s_nop 0
	s_nop 0
	s_nop 0
	s_nop 0
	s_nop 0
	s_add_u32 s10, s28, 0xe000000
	s_addc_u32 s11, s29, 0
	s_lshl_b32 s4, s4, 5
	s_mov_b64 s[12:13], 0x80
	s_and_b32 s15, s4, 0x60
	s_add_i32 m0, s39, 0x18000
	v_lshl_add_u64 v[6:7], v[6:7], 0, s[12:13]
	s_ashr_i32 s60, s3, 31
	s_lshl_b32 s14, s1, 13
	s_lshl_b32 s16, s15, 7
	s_waitcnt vmcnt(4)
	s_barrier
	global_load_lds_dwordx4 v[6:7], off
	v_lshl_add_u64 v[4:5], v[4:5], 0, s[12:13]
	s_add_i32 m0, s39, 0x1a000
	s_add_i32 s61, s39, 0x8000
	s_add_i32 s62, s39, 0xa000
	global_load_lds_dwordx4 v[4:5], off
	v_lshl_add_u64 v[2:3], v[2:3], 0, s[12:13]
	s_mov_b32 m0, s61
	s_add_u32 s4, s42, 0x40080
	global_load_lds_dwordx4 v[2:3], off
	v_lshl_add_u64 v[0:1], v[0:1], 0, s[12:13]
	s_mov_b32 m0, s62
	s_addc_u32 s5, s43, 0
	global_load_lds_dwordx4 v[0:1], off
	s_add_i32 m0, s39, 0x1c000
	v_lshl_add_u64 v[0:1], s[4:5], 0, v[130:131]
	global_load_lds_dwordx4 v[0:1], off
	v_lshl_add_u64 v[0:1], s[4:5], 0, v[134:135]
	s_add_i32 m0, s39, 0x1e000
	s_sext_i32_i8 s69, s0
	global_load_lds_dwordx4 v[0:1], off
	v_and_b32_e32 v0, 15, v208
	v_lshlrev_b32_e32 v1, 1, v11
	v_lshlrev_b32_e32 v2, 6, v208
	s_movk_i32 s0, 0x3c0
	v_lshlrev_b32_e32 v3, 2, v208
	v_and_or_b32 v2, v2, s0, v1
	v_and_b32_e32 v3, 32, v3
	v_lshl_or_b32 v146, s1, 6, v0
	v_lshl_or_b32 v0, v0, 6, v1
	v_lshlrev_b32_e32 v1, 8, v208
	v_bitop3_b32 v147, s16, v2, v3 bitop3:0xf6
	v_and_b32_e32 v1, 0x38000, v1
	v_lshlrev_b32_e32 v2, 11, v10
	v_or3_b32 v1, v8, v1, v2
	v_add_u32_e32 v136, v1, v9
	v_lshlrev_b32_e32 v1, 4, v12
	s_waitcnt vmcnt(6)
	v_and_b32_e32 v1, 0x78000, v1
	v_bitop3_b32 v0, v0, s14, v3 bitop3:0xde
	v_or3_b32 v1, v8, v1, v2
	s_add_i32 s63, 0, 0x10000
	s_add_i32 s64, 0, 0x14000
	v_or_b32_e32 v148, s15, v11
	v_mov_b32_e32 v137, v131
	v_add_u32_e32 v138, v1, v9
	v_mov_b32_e32 v139, v131
	v_mov_b64_e32 v[140:141], 0x1800
	v_mov_b64_e32 v[142:143], 0x17ff
	v_add_u32_e32 v149, s63, v147
	v_add_u32_e32 v150, 0, v0
	v_add_u32_e32 v151, s64, v147
	s_mov_b64 s[14:15], 0x100000
	s_mov_b32 s65, 0x100000
	s_mov_b64 s[16:17], 0x120000
	s_mov_b32 s66, 0x120000
	s_mov_b64 s[18:19], 0x140000
	s_mov_b32 s67, 0x140000
	s_mov_b64 s[20:21], 0x160000
	s_mov_b32 s68, 0x160000
	s_cmpk_lt_u32 s46, 0x100
	s_cbranch_scc1 .Lsprio_2
	s_setprio 1

;     __device__ bool next(int i, Unit& u) const {
;         if (rev && i >= rev) return false;
;         const long L = (long)(rev ? rev - 1 - i : i) * G + c; if (L >= nwg) return false;
;         int wgid = (int)L; { const int q = nwg / NXCD, r = nwg % NXCD, xcd = wgid % NXCD, off = wgid / NXCD; wgid = (xcd < r ? xcd * (q + 1) : r * (q + 1) + (xcd - r) * q) + off; }
;         const int nig = WGM * nN, gid = wgid / nig, fm = gid * WGM, gsz = (nM - fm) < WGM ? (nM - fm) : WGM;
;         u.pm = fm + ((wgid % nig) % gsz); u.pn = (wgid % nig) / gsz; return true;
.LBB0_428:
	s_add_i32 s59, s59, 1
	s_sub_i32 s74, 23, s59
	s_cmpk_eq_i32 s3, 0x100
	s_cselect_b32 s74, s74, s59
	s_mul_i32 s0, s74, s60
	s_mul_hi_u32 s1, s74, s3
	s_add_i32 s1, s1, s0
	s_mul_i32 s0, s74, s3
	s_add_u32 s36, s0, s2
	s_addc_u32 s37, s1, s54
	v_cmp_gt_i64_e64 s[4:5], s[36:37], v[142:143]
	v_cmp_lt_i64_e64 s[0:1], s[36:37], v[140:141]
	s_and_b64 vcc, exec, s[4:5]
	s_cbranch_vccnz .LBB0_430
	s_ashr_i32 s22, s36, 31
	s_lshr_b32 s22, s22, 29
	s_add_i32 s22, s36, s22
	s_ashr_i32 s23, s22, 3
	s_and_b32 s22, s22, -8
	s_sub_i32 s22, s36, s22
	s_cmp_lt_i32 s22, 0
	s_cselect_b32 s24, s55, 0x300
	s_mul_i32 s22, s22, s24
	s_add_i32 s22, s22, s23
	s_ashr_i32 s23, s22, 31
	s_lshr_b32 s23, s23, 25
	s_add_i32 s23, s22, s23
	s_ashr_i32 s24, s23, 7
	s_lshl_b32 s24, s24, 3
	s_and_b32 s23, s23, 0xffffff80
	s_sub_i32 s23, s22, s23
	s_lshr_b32 s22, s23, 3
	s_and_b32 s23, s23, 7
	s_add_i32 s24, s24, s23

; #define PG8_STAGE(bufoff, gbase, voff) do { _Pragma("unroll") for (int _i = 0; _i < 2; ++_i) \
;         __builtin_amdgcn_global_load_lds((const unsigned*)((const char*)(gbase) + (voff)[_i]), (LAS unsigned*)(lds + (bufoff) + ldsw + _i * 8192), 16, 0, 0); } while (0)
; #define PG8_WAIT_V(n) asm volatile("s_waitcnt vmcnt(" #n ")" ::: "memory")
; #define PG8_BAR __builtin_amdgcn_s_barrier()
; template <class Epi, class Ptrs>
; __device__ __forceinline__ void gemm_phase(LAS unsigned char* lds, const int K, const StaticOrder& S, const Ptrs& P, const Epi& E) {
;     ...
;     PG8_STAGE(PG8_SB(0, 0), cB, voffB); PG8_STAGE(PG8_SA(0, 0), cA, voffA); PG8_STAGE(PG8_SB(0, 1), cB + hstep, voffB); PG8_STAGE(PG8_SA(0, 1), cA + hstep, voffA);
;     if (wr == 1) PG8_BAR;
;     PG8_WAIT_V(4); PG8_BAR;
;     PG8_STAGE(PG8_SB(1, 0), cB + kstep, voffB); PG8_STAGE(PG8_SA(1, 0), cA + kstep, voffA); PG8_STAGE(PG8_SB(1, 1), cB + hstep + kstep, voffB);
;     PG8_WAIT_V(6); PG8_BAR;
;     for (;;) {
;         const bool has_next = S.next(ui + 1, nxt);
;         const char* nA = cA; const char* nB = cB; if (has_next) P.get(nxt, nA, nB);
.LBB0_516:
	s_lshl_b32 s1, s1, 5
	s_and_b32 s1, s1, 0x60
	s_lshl_b32 s10, s0, 13
	s_lshl_b32 s11, s1, 7
	s_add_u32 s6, s28, 0x2000000
	s_mov_b64 s[8:9], 0x80
	s_addc_u32 s7, s29, 0
	s_add_i32 m0, s17, 0x18000
	v_lshl_add_u64 v[6:7], v[6:7], 0, s[8:9]
	s_waitcnt vmcnt(4)
	s_barrier
	global_load_lds_dwordx4 v[6:7], off
	v_lshl_add_u64 v[4:5], v[4:5], 0, s[8:9]
	s_add_i32 m0, s17, 0x1a000
	s_add_i32 s28, s17, 0x8000
	s_add_i32 s29, s17, 0xa000
	global_load_lds_dwordx4 v[4:5], off
	v_lshl_add_u64 v[2:3], v[2:3], 0, s[8:9]
	s_mov_b32 m0, s28
	s_add_u32 s4, s22, 0x100080
	global_load_lds_dwordx4 v[2:3], off
	v_lshl_add_u64 v[0:1], v[0:1], 0, s[8:9]
	s_mov_b32 m0, s29
	s_addc_u32 s5, s23, 0
	global_load_lds_dwordx4 v[0:1], off
	s_add_i32 m0, s17, 0x1c000
	v_lshl_add_u64 v[0:1], s[4:5], 0, v[162:163]
	global_load_lds_dwordx4 v[0:1], off
	v_lshl_add_u64 v[0:1], s[4:5], 0, v[166:167]
	s_add_i32 m0, s17, 0x1e000
	v_lshlrev_b32_e32 v2, 6, v208
	global_load_lds_dwordx4 v[0:1], off
	v_and_b32_e32 v0, 15, v208
	v_lshlrev_b32_e32 v1, 1, v11
	s_movk_i32 s4, 0x3c0
	v_lshl_or_b32 v186, s0, 6, v0
	v_and_or_b32 v2, v2, s4, v1
	v_lshlrev_b32_e32 v3, 2, v208
	v_lshl_or_b32 v0, v0, 6, v1
	v_lshlrev_b32_e32 v1, 2, v186
	s_add_i32 s0, 0, 0x20000
	v_and_b32_e32 v3, 32, v3
	v_and_b32_e32 v4, 32, v1
	v_add_u32_e32 v192, s0, v1
	v_lshlrev_b32_e32 v1, 10, v208
	v_bitop3_b32 v187, s11, v2, v3 bitop3:0xf6
	v_and_b32_e32 v1, 0xe0000, v1
	v_lshlrev_b32_e32 v2, 13, v10
	v_or3_b32 v1, v8, v1, v2
	v_add_u32_e32 v168, v1, v9
	v_lshlrev_b32_e32 v1, 6, v12
	s_waitcnt vmcnt(6)
	v_and_b32_e32 v1, 0x1e0000, v1
	v_bitop3_b32 v0, v0, s10, v4 bitop3:0xde
	v_or3_b32 v1, v8, v1, v2
	s_add_i32 s42, 0, 0x10000
	s_add_i32 s43, 0, 0x14000
	v_or_b32_e32 v188, 16, v186
	v_or_b32_e32 v189, 32, v186
	v_or_b32_e32 v190, 48, v186
	v_or_b32_e32 v191, s1, v11
	v_mov_b32_e32 v169, v163
	v_add_u32_e32 v170, v1, v9
	v_mov_b32_e32 v171, v163
	v_mov_b64_e32 v[172:173], 0x600
	v_mov_b64_e32 v[174:175], 0x5ff
	v_add_u32_e32 v193, s42, v187
	v_add_u32_e32 v194, 0, v0
	s_nop 0
	s_nop 0
	s_nop 0
	s_nop 0
	s_nop 0
	s_nop 0
	s_nop 0
	s_nop 0
	s_nop 0
	s_nop 0
	s_nop 0
	s_nop 0
	s_nop 0
	s_nop 0
	s_nop 0
	s_nop 0
	s_nop 0
	s_nop 0
	s_nop 0
	s_nop 0
	s_nop 0
	s_nop 0
	s_nop 0
	s_nop 0
	s_nop 0
	s_nop 0
	s_nop 0
	s_nop 0
	s_nop 0
	s_nop 0
	s_nop 0
	s_nop 0
	s_nop 0
	s_nop 0
	s_nop 0
	s_nop 0
	s_nop 0
	s_nop 0
	s_nop 0
	s_nop 0
	s_nop 0
	s_nop 0
	s_nop 0
	s_nop 0
	s_nop 0
	s_nop 0
	s_nop 0
	s_nop 0
	s_nop 0
	s_nop 0
	s_nop 0
	s_nop 0
	s_nop 0
	s_nop 0
	s_nop 0
	v_add_u32_e32 v195, s43, v187
	s_cmpk_lt_u32 s33, 0x100
	s_cbranch_scc1 .Lsprio_3
	s_setprio 1

;     __device__ bool next(int i, Unit& u) const {
;         if (rev && i >= rev) return false;
;         const long L = (long)(rev ? rev - 1 - i : i) * G + c; if (L >= nwg) return false;
;         int wgid = (int)L; { const int q = nwg / NXCD, r = nwg % NXCD, xcd = wgid % NXCD, off = wgid / NXCD; wgid = (xcd < r ? xcd * (q + 1) : r * (q + 1) + (xcd - r) * q) + off; }
;         const int nig = WGM * nN, gid = wgid / nig, fm = gid * WGM, gsz = (nM - fm) < WGM ? (nM - fm) : WGM;
;         u.pm = fm + ((wgid % nig) % gsz); u.pn = (wgid % nig) / gsz; return true;
.LBB0_517:
	s_add_i32 s44, s45, 1
	s_mul_i32 s0, s44, s30
	s_mul_hi_u32 s1, s44, s3
	s_add_i32 s1, s1, s0
	s_mul_i32 s0, s44, s3
	s_add_u32 s14, s0, s2
	s_addc_u32 s15, s1, s31
	v_cmp_gt_i64_e64 s[0:1], s[14:15], v[174:175]
	v_cmp_lt_i64_e64 s[4:5], s[14:15], v[172:173]
	s_and_b64 vcc, exec, s[0:1]
	s_cbranch_vccnz .LBB0_519
	s_ashr_i32 s10, s14, 31
	s_lshr_b32 s10, s10, 29
	s_add_i32 s10, s14, s10
	s_ashr_i32 s11, s10, 3
	s_and_b32 s10, s10, -8
	s_sub_i32 s10, s14, s10
	s_cmp_lt_i32 s10, 0
	s_cselect_b32 s12, s39, 0xc0
	s_mul_i32 s10, s10, s12
	s_add_i32 s10, s10, s11
	s_ashr_i32 s11, s10, 31
	s_lshr_b32 s11, s11, 27
	s_add_i32 s11, s10, s11
	s_ashr_i32 s12, s11, 5
	s_lshl_b32 s12, s12, 3
	s_andn2_b32 s11, s11, 31
	s_sub_i32 s11, s10, s11
	s_lshr_b32 s10, s11, 3
	s_and_b32 s11, s11, 7
	s_add_i32 s12, s12, s11
